# P1 GEMM on 240 WGs (8 rounds), 16 converter WGs run 21504 deferred conversion items; PLE GEMM in P3b
# speedup vs baseline: 1.0074x; 1.0031x over previous
.LBB0_9:
	s_cmp_lg_u32 s101, 0
	s_cbranch_scc1 .Lcv_go
	s_cmp_lt_i32 s80, 0x15680
	s_cbranch_scc1 .Lcv_go
	s_cmp_lt_i32 s80, 0x1aa80
	s_cbranch_scc1 .LBB0_8

.LBB0_109:
	s_or_b64 exec, exec, s[0:1]
	v_writelane_b32 v250, s86, 10
	s_waitcnt lgkmcnt(0)
	s_barrier
	v_writelane_b32 v250, s87, 11
	v_mbcnt_lo_u32_b32 v0, -1, 0
	v_mbcnt_hi_u32_b32 v0, -1, v0
	s_cmpk_eq_i32 s88, 0x100
	s_cselect_b32 s99, 0xf0, s88
	s_min_i32 s98, s99, 0x774
	s_cmp_lt_i32 s2, s98
	s_load_dwordx4 s[28:31], s[86:87], 0xb8
	s_cselect_b64 s[0:1], -1, 0
	v_mbcnt_lo_u32_b32 v8, -1, 0
	v_mbcnt_hi_u32_b32 v8, -1, v8
	s_and_b64 vcc, exec, s[0:1]
	s_cbranch_vccz .LBB0_111
	s_ashr_i32 s4, s2, 31
	s_lshr_b32 s4, s4, 29
	s_add_i32 s4, s2, s4
	s_and_b32 s5, s4, -8
	s_sub_i32 s5, s2, s5
	s_mul_i32 s7, s5, 0xee
	s_add_i32 s7, s7, 4
	s_ashr_i32 s4, s4, 3
	s_mul_i32 s6, s5, 0xef
	s_cmp_lt_i32 s5, 4
	s_cselect_b32 s5, s6, s7
	s_add_i32 s5, s5, s4
	s_mul_hi_i32 s4, s5, 0x4d4873ed
	s_lshr_b32 s6, s4, 31
	s_ashr_i32 s4, s4, 7
	s_add_i32 s4, s4, s6
	s_lshl_b32 s6, s4, 3
	s_sub_i32 s7, 36, s6
	s_mulk_i32 s4, 0x1a8
	s_min_u32 s7, s7, 8
	s_sub_i32 s8, s5, s4
	s_sext_i32_i16 s4, s8
	v_cvt_f32_ubyte0_e32 v1, s7
	v_cvt_f32_i32_e32 v0, s4
	v_rcp_iflag_f32_e32 v2, v1
	s_ashr_i32 s4, s4, 30
	s_or_b32 s9, s4, 1
	v_mul_f32_e32 v2, v0, v2
	v_trunc_f32_e32 v2, v2
	v_fma_f32 v0, -v2, v1, v0
	v_cvt_i32_f32_e32 v2, v2
	v_cmp_ge_f32_e64 s[4:5], |v0|, v1
	s_and_b64 s[4:5], s[4:5], exec
	s_cselect_b32 s4, s9, 0
	v_readfirstlane_b32 s5, v2
	s_add_i32 s4, s5, s4
	s_sext_i32_i16 s14, s4
	s_mul_i32 s4, s4, s7
	s_sub_i32 s4, s8, s4
	s_sext_i32_i16 s4, s4
	s_add_i32 s20, s6, s4

.LBB0_399:
	s_cmpk_eq_i32 s88, 0x100
	s_cselect_b64 s[0:1], -1, 0
	s_cmpk_lg_i32 s88, 0x100
	v_writelane_b32 v250, s0, 23
	s_cselect_b64 s[22:23], -1, 0
	s_cmp_lt_i32 s2, s99
	v_writelane_b32 v250, s1, 24
	s_cselect_b64 s[0:1], -1, 0
	s_or_b64 s[0:1], s[0:1], s[22:23]
	s_and_b64 vcc, exec, s[0:1]
	s_cbranch_vccnz .LBB0_416
	v_writelane_b32 v248, s0, 0
	v_writelane_b32 v248, s1, 1
	v_writelane_b32 v248, s2, 2
	v_writelane_b32 v248, s3, 3
	v_writelane_b32 v248, s4, 4
	v_writelane_b32 v248, s5, 5
	v_writelane_b32 v248, s6, 6
	v_writelane_b32 v248, s7, 7
	v_writelane_b32 v248, s8, 8
	v_writelane_b32 v248, s9, 9
	v_writelane_b32 v248, s10, 10
	v_writelane_b32 v248, s11, 11
	v_writelane_b32 v248, s12, 12
	v_writelane_b32 v248, s13, 13
	v_writelane_b32 v248, s14, 14
	v_writelane_b32 v248, s15, 15
	v_writelane_b32 v248, s16, 16
	v_writelane_b32 v248, s17, 17
	v_writelane_b32 v248, s18, 18
	v_writelane_b32 v248, s19, 19
	v_writelane_b32 v248, s20, 20
	v_writelane_b32 v248, s21, 21
	v_writelane_b32 v248, s22, 22
	v_writelane_b32 v248, s23, 23
	v_writelane_b32 v248, s24, 24
	v_writelane_b32 v248, s25, 25
	v_writelane_b32 v248, s26, 26
	v_writelane_b32 v248, s27, 27
	v_writelane_b32 v248, s28, 28
	v_writelane_b32 v248, s29, 29
	v_writelane_b32 v248, s30, 30
	v_writelane_b32 v248, s31, 31
	v_writelane_b32 v248, s32, 32
	v_writelane_b32 v248, s33, 33
	v_writelane_b32 v248, s34, 34
	v_writelane_b32 v248, s35, 35
	v_writelane_b32 v248, s36, 36
	v_writelane_b32 v248, s37, 37
	v_writelane_b32 v248, s38, 38
	v_writelane_b32 v248, s39, 39
	v_writelane_b32 v248, s40, 40
	v_writelane_b32 v248, s41, 41
	v_writelane_b32 v248, s42, 42
	v_writelane_b32 v248, s43, 43
	v_writelane_b32 v248, s44, 44
	v_writelane_b32 v248, s45, 45
	v_writelane_b32 v248, s46, 46
	v_writelane_b32 v248, s47, 47
	v_writelane_b32 v248, s48, 48
	v_writelane_b32 v248, s49, 49
	v_writelane_b32 v248, s50, 50
	v_writelane_b32 v248, s51, 51
	v_writelane_b32 v248, s52, 52
	v_writelane_b32 v248, s53, 53
	v_writelane_b32 v248, s54, 54
	v_writelane_b32 v248, s55, 55
	v_writelane_b32 v248, s56, 56
	v_writelane_b32 v248, s57, 57
	v_writelane_b32 v248, s58, 58
	v_writelane_b32 v248, s59, 59
	v_writelane_b32 v248, s60, 60
	v_writelane_b32 v248, s61, 61
	v_writelane_b32 v248, s62, 62
	v_writelane_b32 v248, s63, 63
	v_writelane_b32 v249, s64, 0
	v_writelane_b32 v249, s65, 1
	v_writelane_b32 v249, s66, 2
	v_writelane_b32 v249, s67, 3
	v_writelane_b32 v249, s68, 4
	v_writelane_b32 v249, s69, 5
	v_writelane_b32 v249, s70, 6
	v_writelane_b32 v249, s71, 7
	v_writelane_b32 v249, s72, 8
	v_writelane_b32 v249, s73, 9
	v_writelane_b32 v249, s74, 10
	v_writelane_b32 v249, s75, 11
	v_writelane_b32 v249, s76, 12
	v_writelane_b32 v249, s77, 13
	v_writelane_b32 v249, s78, 14
	v_writelane_b32 v249, s79, 15
	v_writelane_b32 v249, s80, 16
	v_writelane_b32 v249, s81, 17
	v_writelane_b32 v249, s82, 18
	v_writelane_b32 v249, s83, 19
	v_writelane_b32 v249, s84, 20
	v_writelane_b32 v249, s85, 21
	v_writelane_b32 v249, s86, 22
	v_writelane_b32 v249, s87, 23
	v_writelane_b32 v249, s88, 24
	v_writelane_b32 v249, s89, 25
	v_writelane_b32 v249, s90, 26
	v_writelane_b32 v249, s91, 27
	v_writelane_b32 v249, s92, 28
	v_writelane_b32 v249, s93, 29
	v_writelane_b32 v249, s94, 30
	v_writelane_b32 v249, s95, 31
	v_writelane_b32 v249, s96, 32
	v_writelane_b32 v249, s97, 33
	v_readlane_b32 s1, v250, 9
	v_readlane_b32 s86, v250, 10
	v_readlane_b32 s87, v250, 11
	s_sub_i32 s0, s2, s99
	s_lshl_b32 s0, s0, 3
	s_nop 1
	s_add_i32 s12, s0, s1
	s_add_i32 s12, s12, 0x15680
	s_movk_i32 s14, 0x80
	s_mov_b32 s100, 0x1aa80
	s_mov_b32 s101, 1
	s_branch .Lcv_entry
